# speedup vs baseline: 1.0088x; 1.0003x over previous
; #define GAS __attribute__((address_space(1)))
; __device__ __forceinline__ uint2 ldnt_u2(const void* q) { u32x2_t v = __builtin_nontemporal_load((const u32x2_t*)q); return make_uint2(v[0], v[1]); }
; __device__ __forceinline__ void sgu_item(PP p, Ctx cx, int g0, int rb_l, int chunk, int tseq, bool samp, int sb, char* smem) {
;     ...
;     bf16x8 bfr[4][2];
; #pragma unroll
;     for (int kk = 0; kk < 4; ++kk)
; #pragma unroll
;       for (int ni = 0; ni < 2; ++ni)
;         if (kk <= kk_max)
;           bfr[kk][ni] = *(GAS const bf16x8*)(Wsb + ((size_t)(g * 128 + t0 + ni * 16 + fr)) * 128 + kk * 32 + fq * 8);
;     uint2 uv[2][4];
;     float bsv[2];
; #pragma unroll
;     for (int ni = 0; ni < 2; ++ni) {
;       int t = t0 + ni * 16 + fr;
;       bsv[ni] = p->b_s[g * 128 + t];
; #pragma unroll
;       for (int mi = 0; mi < 4; ++mi)
;         uv[ni][mi] = (t < nrows) ? ldnt_u2(Ub + (size_t)(r0 + t) * 1024 + g * 128 + c0 + mi * 16 + fq * 4) : make_uint2(0, 0);
;     }
;     __syncthreads();
; #pragma unroll
;     for (int i = 0; i < 4; ++i) {
;       int e = tid + i * 512;
;       int s = e >> 4, cc = (e & 15) * 8;
;       float vn[8];
;       if (s < nrows) {
;         float lg[8], lb[8];
;         ld8f(p->ln_g + g * 128 + cc, lg);
;         ld8f(p->ln_b + g * 128 + cc, lb);
.LBB0_410:
	s_load_dwordx4 s[20:23], s[0:1], 0x38
	s_waitcnt lgkmcnt(0)
	v_lshl_add_u64 v[170:171], s[20:21], 0, v[110:111]
	v_lshl_add_u64 v[172:173], s[22:23], 0, v[110:111]
	v_lshl_add_u64 v[170:171], v[170:171], 0, s[94:95]
	v_lshl_add_u64 v[172:173], v[172:173], 0, s[94:95]
	global_load_dwordx4 v[238:241], v[170:171], off
	global_load_dwordx4 v[242:245], v[170:171], off offset:16
	global_load_dwordx4 v[246:249], v[172:173], off
	global_load_dwordx4 v[250:253], v[172:173], off offset:16
	s_and_saveexec_b64 s[58:59], s[4:5]
	s_cbranch_execz .LBB0_418
	v_mov_b32_e32 v149, v0
	v_lshlrev_b64 v[2:3], 8, v[148:149]
	v_lshl_add_u64 v[2:3], v[96:97], 0, v[2:3]
	global_load_dwordx4 v[48:51], v[2:3], off
	s_or_b64 exec, exec, s[58:59]
	v_add_u32_e32 v2, 16, v148
	s_and_saveexec_b64 s[58:59], s[4:5]
	s_cbranch_execnz .LBB0_419

; #define GAS __attribute__((address_space(1)))
; __device__ __forceinline__ u16 f2bf(float f) { return (u16)(pack2(f, 0.f) & 0xffffu); }
; __device__ __forceinline__ float bf2f(u16 b) { return __uint_as_float(((uint32_t)b) << 16); }
; __device__ __forceinline__ void sgu_item(PP p, Ctx cx, int g0, int rb_l, int chunk, int tseq, bool samp, int sb, char* smem) {
;     ...
;     for (int i = 0; i < 4; ++i) {
;       int e = tid + i * 512;
;       int s = e >> 4, cc = (e & 15) * 8;
;       float vn[8];
;       if (s < nrows) {
;         float lg[8], lb[8];
;         ld8f(p->ln_g + g * 128 + cc, lg);
;         ld8f(p->ln_b + g * 128 + cc, lb);
;         float mu = stats[s * 2], rstd = stats[s * 2 + 1];
;         unsigned w[4] = {tl[i].x, tl[i].y, tl[i].z, tl[i].w};
; #pragma unroll
;         for (int k = 0; k < 4; ++k) {
;           vn[2 * k] = (bf2f((u16)(w[k] & 0xffff)) - mu) * rstd * lg[2 * k] + lb[2 * k];
;           vn[2 * k + 1] = (bf2f((u16)(w[k] >> 16)) - mu) * rstd * lg[2 * k + 1] + lb[2 * k + 1];
;         }
;         if (samp) {
;           float* o = p->out + O_GV + ((size_t)sb * DSEQ + s) * 1024 + g * 128 + cc;
;           *(GAS float4*)(o) = make_float4(vn[0], vn[1], vn[2], vn[3]);
;           *(GAS float4*)(o + 4) = make_float4(vn[4], vn[5], vn[6], vn[7]);
;         }
;       } else {
; #pragma unroll
;         for (int k = 0; k < 8; ++k) vn[k] = 0.f;
;       }
;       int soff = ((((s >> 3) ^ ((cc >> 3) & 15)) << 3) + (s & 7));
; #pragma unroll
;       for (int k = 0; k < 8; ++k) vT[(cc + k) * LDV + soff] = f2bf(vn[k]);
.LBB0_442:
	s_or_b64 exec, exec, s[58:59]
	v_mov_b32_e32 v52, 0
	v_mov_b32_e32 v54, 0
	v_mov_b32_e32 v55, 0
	v_mov_b32_e32 v56, 0
	v_mov_b32_e32 v57, 0
	v_mov_b32_e32 v58, 0
	v_mov_b32_e32 v59, 0
	v_mov_b32_e32 v60, 0
	v_mov_b32_e32 v61, 0
	s_waitcnt lgkmcnt(0)
	s_barrier
	s_and_saveexec_b64 s[66:67], s[12:13]
	s_cbranch_execz .LBB0_444
	ds_read_b64 v[70:71], v214 offset:32768
	s_waitcnt lgkmcnt(0)
	s_load_dwordx2 s[20:21], s[0:1], 0xb8
	s_waitcnt lgkmcnt(0)
	v_lshl_add_u64 v[54:55], s[20:21], 0, v[108:109]
	v_lshl_add_u64 v[72:73], v[54:55], 0, s[94:95]
	s_nop 0
	v_lshlrev_b32_e32 v2, 16, v4
	v_and_b32_e32 v3, 0xffff0000, v4
	v_pk_add_f32 v[2:3], v[2:3], v[70:71] op_sel_hi:[1,0] neg_lo:[0,1] neg_hi:[0,1]
	s_nop 0
	v_pk_mul_f32 v[2:3], v[70:71], v[2:3] op_sel:[1,0]
	s_waitcnt vmcnt(0)
	v_pk_fma_f32 v[54:55], v[238:239], v[2:3], v[246:247]
	v_lshlrev_b32_e32 v2, 16, v5
	v_and_b32_e32 v3, 0xffff0000, v5
	v_pk_add_f32 v[2:3], v[2:3], v[70:71] op_sel_hi:[1,0] neg_lo:[0,1] neg_hi:[0,1]
	s_nop 0
	v_pk_mul_f32 v[2:3], v[70:71], v[2:3] op_sel:[1,0]
	s_nop 0
	v_pk_fma_f32 v[56:57], v[240:241], v[2:3], v[248:249]
	v_lshlrev_b32_e32 v2, 16, v6
	v_and_b32_e32 v3, 0xffff0000, v6
	v_pk_add_f32 v[2:3], v[2:3], v[70:71] op_sel_hi:[1,0] neg_lo:[0,1] neg_hi:[0,1]
	s_nop 0
	v_pk_mul_f32 v[2:3], v[70:71], v[2:3] op_sel:[1,0]
	s_nop 0
	v_pk_fma_f32 v[58:59], v[242:243], v[2:3], v[250:251]
	v_lshlrev_b32_e32 v2, 16, v7
	v_and_b32_e32 v3, 0xffff0000, v7
	v_pk_add_f32 v[2:3], v[2:3], v[70:71] op_sel_hi:[1,0] neg_lo:[0,1] neg_hi:[0,1]
	s_nop 0
	v_pk_mul_f32 v[2:3], v[70:71], v[2:3] op_sel:[1,0]
	s_nop 0
	v_pk_fma_f32 v[60:61], v[244:245], v[2:3], v[252:253]
	global_store_dwordx4 v[72:73], v[54:57], off offset:-16
	global_store_dwordx4 v[72:73], v[58:61], off
.LBB0_444:
	s_or_b64 exec, exec, s[66:67]
	v_cvt_pk_bf16_f32 v1, v54, s0
	ds_write_b16 v95, v1
	v_cvt_pk_bf16_f32 v1, v55, s0
	ds_write_b16 v95, v1 offset:256
	v_cvt_pk_bf16_f32 v1, v56, s0
	ds_write_b16 v95, v1 offset:512
	v_cvt_pk_bf16_f32 v1, v57, s0
	ds_write_b16 v95, v1 offset:768
	v_cvt_pk_bf16_f32 v1, v58, s0
	ds_write_b16 v95, v1 offset:1024
	v_cvt_pk_bf16_f32 v1, v59, s0
	ds_write_b16 v95, v1 offset:1280
	v_cvt_pk_bf16_f32 v1, v60, s0
	ds_write_b16 v95, v1 offset:1536
	v_cvt_pk_bf16_f32 v1, v61, s0
	v_mov_b32_e32 v53, 0
	v_mov_b32_e32 v54, 0
	v_mov_b32_e32 v55, 0
	v_mov_b32_e32 v56, 0
	v_mov_b32_e32 v57, 0
	v_mov_b32_e32 v58, 0
	v_mov_b32_e32 v59, 0
	ds_write_b16 v95, v1 offset:1792
	s_and_saveexec_b64 s[66:67], s[14:15]
	s_cbranch_execz .LBB0_446
	ds_read_b64 v[68:69], v87 offset:32768
	s_waitcnt lgkmcnt(0)
	s_load_dwordx2 s[20:21], s[0:1], 0xb8
	s_waitcnt lgkmcnt(0)
	v_lshl_add_u64 v[52:53], s[20:21], 0, v[118:119]
	v_lshl_add_u64 v[70:71], v[52:53], 0, s[94:95]
	s_nop 0
	v_lshlrev_b32_e32 v2, 16, v8
	v_and_b32_e32 v3, 0xffff0000, v8
	v_pk_add_f32 v[2:3], v[2:3], v[68:69] op_sel_hi:[1,0] neg_lo:[0,1] neg_hi:[0,1]
	s_nop 0
	v_pk_mul_f32 v[2:3], v[68:69], v[2:3] op_sel:[1,0]
	v_pk_fma_f32 v[52:53], v[238:239], v[2:3], v[246:247]
	v_lshlrev_b32_e32 v2, 16, v9
	v_and_b32_e32 v3, 0xffff0000, v9
	v_pk_add_f32 v[2:3], v[2:3], v[68:69] op_sel_hi:[1,0] neg_lo:[0,1] neg_hi:[0,1]
	s_nop 0
	v_pk_mul_f32 v[2:3], v[68:69], v[2:3] op_sel:[1,0]
	s_nop 0
	v_pk_fma_f32 v[54:55], v[240:241], v[2:3], v[248:249]
	v_lshlrev_b32_e32 v2, 16, v10
	v_and_b32_e32 v3, 0xffff0000, v10
	v_pk_add_f32 v[2:3], v[2:3], v[68:69] op_sel_hi:[1,0] neg_lo:[0,1] neg_hi:[0,1]
	s_nop 0
	v_pk_mul_f32 v[2:3], v[68:69], v[2:3] op_sel:[1,0]
	s_nop 0
	v_pk_fma_f32 v[56:57], v[242:243], v[2:3], v[250:251]
	v_lshlrev_b32_e32 v2, 16, v11
	v_and_b32_e32 v3, 0xffff0000, v11
	v_pk_add_f32 v[2:3], v[2:3], v[68:69] op_sel_hi:[1,0] neg_lo:[0,1] neg_hi:[0,1]
	s_nop 0
	v_pk_mul_f32 v[2:3], v[68:69], v[2:3] op_sel:[1,0]
	s_nop 0
	v_pk_fma_f32 v[58:59], v[244:245], v[2:3], v[252:253]
	global_store_dwordx4 v[70:71], v[52:55], off offset:-16
	global_store_dwordx4 v[70:71], v[56:59], off
; #define GAS __attribute__((address_space(1)))
; __device__ __forceinline__ u16 f2bf(float f) { return (u16)(pack2(f, 0.f) & 0xffffu); }
; __device__ __forceinline__ float bf2f(u16 b) { return __uint_as_float(((uint32_t)b) << 16); }
; __device__ __forceinline__ void sgu_item(PP p, Ctx cx, int g0, int rb_l, int chunk, int tseq, bool samp, int sb, char* smem) {
;     ...
;     for (int i = 0; i < 4; ++i) {
;       int e = tid + i * 512;
;       int s = e >> 4, cc = (e & 15) * 8;
;       float vn[8];
;       if (s < nrows) {
;         float lg[8], lb[8];
;         ld8f(p->ln_g + g * 128 + cc, lg);
;         ld8f(p->ln_b + g * 128 + cc, lb);
;         float mu = stats[s * 2], rstd = stats[s * 2 + 1];
;         unsigned w[4] = {tl[i].x, tl[i].y, tl[i].z, tl[i].w};
; #pragma unroll
;         for (int k = 0; k < 4; ++k) {
;           vn[2 * k] = (bf2f((u16)(w[k] & 0xffff)) - mu) * rstd * lg[2 * k] + lb[2 * k];
;           vn[2 * k + 1] = (bf2f((u16)(w[k] >> 16)) - mu) * rstd * lg[2 * k + 1] + lb[2 * k + 1];
;         }
;         if (samp) {
;           float* o = p->out + O_GV + ((size_t)sb * DSEQ + s) * 1024 + g * 128 + cc;
;           *(GAS float4*)(o) = make_float4(vn[0], vn[1], vn[2], vn[3]);
;           *(GAS float4*)(o + 4) = make_float4(vn[4], vn[5], vn[6], vn[7]);
;         }
;       } else {
; #pragma unroll
;         for (int k = 0; k < 8; ++k) vn[k] = 0.f;
;       }
;       int soff = ((((s >> 3) ^ ((cc >> 3) & 15)) << 3) + (s & 7));
; #pragma unroll
;       for (int k = 0; k < 8; ++k) vT[(cc + k) * LDV + soff] = f2bf(vn[k]);
.LBB0_446:
	s_or_b64 exec, exec, s[66:67]
	v_cvt_pk_bf16_f32 v1, v52, s0
	ds_write_b16 v230, v1
	v_cvt_pk_bf16_f32 v1, v53, s0
	ds_write_b16 v230, v1 offset:256
	v_cvt_pk_bf16_f32 v1, v54, s0
	ds_write_b16 v230, v1 offset:512
	v_cvt_pk_bf16_f32 v1, v55, s0
	ds_write_b16 v230, v1 offset:768
	v_cvt_pk_bf16_f32 v1, v56, s0
	ds_write_b16 v230, v1 offset:1024
	v_cvt_pk_bf16_f32 v1, v57, s0
	ds_write_b16 v230, v1 offset:1280
	v_cvt_pk_bf16_f32 v1, v58, s0
	ds_write_b16 v230, v1 offset:1536
	v_cvt_pk_bf16_f32 v1, v59, s0
	v_mov_b32_e32 v52, 0
	v_mov_b32_e32 v54, 0
	v_mov_b32_e32 v55, 0
	v_mov_b32_e32 v56, 0
	v_mov_b32_e32 v57, 0
	v_mov_b32_e32 v58, 0
	v_mov_b32_e32 v59, 0
	v_mov_b32_e32 v60, 0
	v_mov_b32_e32 v61, 0
	ds_write_b16 v230, v1 offset:1792
	s_and_saveexec_b64 s[66:67], s[16:17]
	s_cbranch_execz .LBB0_448
	ds_read_b64 v[70:71], v89 offset:32768
	s_waitcnt lgkmcnt(0)
	s_load_dwordx2 s[20:21], s[0:1], 0xb8
	s_waitcnt lgkmcnt(0)
	v_lshl_add_u64 v[54:55], s[20:21], 0, v[122:123]
	v_lshl_add_u64 v[72:73], v[54:55], 0, s[94:95]
	s_nop 0
	v_lshlrev_b32_e32 v2, 16, v12
	v_and_b32_e32 v3, 0xffff0000, v12
	v_pk_add_f32 v[2:3], v[2:3], v[70:71] op_sel_hi:[1,0] neg_lo:[0,1] neg_hi:[0,1]
	s_nop 0
	v_pk_mul_f32 v[2:3], v[70:71], v[2:3] op_sel:[1,0]
	v_pk_fma_f32 v[54:55], v[238:239], v[2:3], v[246:247]
	v_lshlrev_b32_e32 v2, 16, v13
	v_and_b32_e32 v3, 0xffff0000, v13
	v_pk_add_f32 v[2:3], v[2:3], v[70:71] op_sel_hi:[1,0] neg_lo:[0,1] neg_hi:[0,1]
	s_nop 0
	v_pk_mul_f32 v[2:3], v[70:71], v[2:3] op_sel:[1,0]
	s_nop 0
	v_pk_fma_f32 v[56:57], v[240:241], v[2:3], v[248:249]
	v_lshlrev_b32_e32 v2, 16, v14
	v_and_b32_e32 v3, 0xffff0000, v14
	v_pk_add_f32 v[2:3], v[2:3], v[70:71] op_sel_hi:[1,0] neg_lo:[0,1] neg_hi:[0,1]
	s_nop 0
	v_pk_mul_f32 v[2:3], v[70:71], v[2:3] op_sel:[1,0]
	s_nop 0
	v_pk_fma_f32 v[58:59], v[242:243], v[2:3], v[250:251]
	v_lshlrev_b32_e32 v2, 16, v15
	v_and_b32_e32 v3, 0xffff0000, v15
	v_pk_add_f32 v[2:3], v[2:3], v[70:71] op_sel_hi:[1,0] neg_lo:[0,1] neg_hi:[0,1]
	s_nop 0
	v_pk_mul_f32 v[2:3], v[70:71], v[2:3] op_sel:[1,0]
	s_nop 0
	v_pk_fma_f32 v[60:61], v[244:245], v[2:3], v[252:253]
	global_store_dwordx4 v[72:73], v[54:57], off offset:-16
	global_store_dwordx4 v[72:73], v[58:61], off
.LBB0_448:
	s_or_b64 exec, exec, s[66:67]
	v_cvt_pk_bf16_f32 v1, v54, s0
	ds_write_b16 v231, v1
	v_cvt_pk_bf16_f32 v1, v55, s0
	ds_write_b16 v231, v1 offset:256
	v_cvt_pk_bf16_f32 v1, v56, s0
	ds_write_b16 v231, v1 offset:512
	v_cvt_pk_bf16_f32 v1, v57, s0
	ds_write_b16 v231, v1 offset:768
	v_cvt_pk_bf16_f32 v1, v58, s0
	ds_write_b16 v231, v1 offset:1024
	v_cvt_pk_bf16_f32 v1, v59, s0
	ds_write_b16 v231, v1 offset:1280
	v_cvt_pk_bf16_f32 v1, v60, s0
	ds_write_b16 v231, v1 offset:1536
	v_cvt_pk_bf16_f32 v1, v61, s0
	v_mov_b32_e32 v53, 0
	v_mov_b32_e32 v54, 0
	v_mov_b32_e32 v55, 0
	v_mov_b32_e32 v56, 0
	v_mov_b32_e32 v57, 0
	v_mov_b32_e32 v58, 0
	v_mov_b32_e32 v59, 0
	ds_write_b16 v231, v1 offset:1792
	s_and_saveexec_b64 s[66:67], s[18:19]
	s_cbranch_execz .LBB0_450
	ds_read_b64 v[68:69], v91 offset:32768
	s_waitcnt lgkmcnt(0)
	s_load_dwordx2 s[20:21], s[0:1], 0xb8
	s_waitcnt lgkmcnt(0)
	v_lshl_add_u64 v[52:53], s[20:21], 0, v[128:129]
	v_lshl_add_u64 v[70:71], v[52:53], 0, s[94:95]
	s_nop 0
	v_lshlrev_b32_e32 v2, 16, v16
	v_and_b32_e32 v3, 0xffff0000, v16
	v_pk_add_f32 v[2:3], v[2:3], v[68:69] op_sel_hi:[1,0] neg_lo:[0,1] neg_hi:[0,1]
	s_nop 0
	v_pk_mul_f32 v[2:3], v[68:69], v[2:3] op_sel:[1,0]
	v_pk_fma_f32 v[52:53], v[238:239], v[2:3], v[246:247]
	v_lshlrev_b32_e32 v2, 16, v17
	v_and_b32_e32 v3, 0xffff0000, v17
	v_pk_add_f32 v[2:3], v[2:3], v[68:69] op_sel_hi:[1,0] neg_lo:[0,1] neg_hi:[0,1]
	s_nop 0
	v_pk_mul_f32 v[2:3], v[68:69], v[2:3] op_sel:[1,0]
	s_nop 0
	v_pk_fma_f32 v[54:55], v[240:241], v[2:3], v[248:249]
	v_lshlrev_b32_e32 v2, 16, v18
	v_and_b32_e32 v3, 0xffff0000, v18
	v_pk_add_f32 v[2:3], v[2:3], v[68:69] op_sel_hi:[1,0] neg_lo:[0,1] neg_hi:[0,1]
	s_nop 0
	v_pk_mul_f32 v[2:3], v[68:69], v[2:3] op_sel:[1,0]
	s_nop 0
	v_pk_fma_f32 v[56:57], v[242:243], v[2:3], v[250:251]
	v_lshlrev_b32_e32 v2, 16, v19
	v_and_b32_e32 v3, 0xffff0000, v19
	v_pk_add_f32 v[2:3], v[2:3], v[68:69] op_sel_hi:[1,0] neg_lo:[0,1] neg_hi:[0,1]
	s_nop 0
	v_pk_mul_f32 v[2:3], v[68:69], v[2:3] op_sel:[1,0]
	s_nop 0
	v_pk_fma_f32 v[58:59], v[244:245], v[2:3], v[252:253]
	global_store_dwordx4 v[70:71], v[52:55], off offset:-16
	global_store_dwordx4 v[70:71], v[56:59], off
